# FoX loop top: next-tile loads issued right after each staging ds_write
# baseline (speedup 1.0000x reference)
.LBB0_946:
	s_mul_i32 s37, s6, 0x4800
	s_waitcnt vmcnt(7)
	s_cmp_eq_u32 s44, 64
	s_cbranch_scc1 .Lfox_top_last
	v_add3_u32 v50, s37, v132, v133
	v_lshl_add_u64 v[52:53], v[118:119], 0, v[116:117]
	s_waitcnt vmcnt(3)
	ds_write_b128 v50, v[98:101] offset:32768
	global_load_dwordx4 v[98:101], v[52:53], off
	v_add_u32_e32 v50, s37, v134
	v_add3_u32 v50, v50, v133, s95
	v_lshl_add_u64 v[52:53], v[122:123], 0, v[116:117]
	s_waitcnt vmcnt(3)
	ds_write2_b64 v50, v[102:103], v[104:105] offset1:1
	global_load_dwordx4 v[102:105], v[52:53], off
	v_add3_u32 v50, s37, v130, v133
	v_lshl_add_u64 v[52:53], v[124:125], 0, v[116:117]
	s_waitcnt vmcnt(3)
	ds_write_b128 v50, v[106:109] offset:32768
	global_load_dwordx4 v[106:109], v[52:53], off
	v_add_u32_e32 v50, s37, v131
	v_add3_u32 v50, v50, v133, s95
	v_lshl_add_u64 v[52:53], v[120:121], 0, v[116:117]
	s_waitcnt vmcnt(3)
	ds_write2_b64 v50, v[110:111], v[112:113] offset1:1
	global_load_dwordx4 v[110:113], v[52:53], off
	s_branch .LBB0_948
.Lfox_top_last:
	v_add3_u32 v50, s37, v132, v133
	s_waitcnt vmcnt(3)
	ds_write_b128 v50, v[98:101] offset:32768
	v_add_u32_e32 v50, s37, v134
	v_add3_u32 v50, v50, v133, s95
	s_waitcnt vmcnt(2)
	ds_write2_b64 v50, v[102:103], v[104:105] offset1:1
	v_add3_u32 v50, s37, v130, v133
	s_waitcnt vmcnt(1)
	ds_write_b128 v50, v[106:109] offset:32768
	v_add_u32_e32 v50, s37, v131
	v_add3_u32 v50, v50, v133, s95
	s_waitcnt vmcnt(0)
	ds_write2_b64 v50, v[110:111], v[112:113] offset1:1
